# UQ epilogue: waits that only had stores issued after the last load now use vmcnt(k) instead of draining those k stores
# speedup vs baseline: 1.0139x; 1.0139x over previous
; __device__ __forceinline__ void rope8v(float (&v)[8], f32x4 c0, f32x4 c1) {
;   const float cs[8] = {c0[0], c0[1], c0[2], c0[3], c1[0], c1[1], c1[2], c1[3]};
; #pragma unroll
;   for (int i = 0; i < 4; ++i) { const float x1 = v[2 * i], x2 = v[2 * i + 1]; v[2 * i] = x1 * cs[2 * i] - x2 * cs[2 * i + 1]; v[2 * i + 1] = x2 * cs[2 * i] + x1 * cs[2 * i + 1]; }
; }
;   __device__ __forceinline__ void emit(const EpiPre& q0, int row, int col, f32x4 a, f32x4 b, const f32x4 (&hb)[2][2], const float (&hs)[2][4], int ai_, int m_, int bj_) const {
;     ...
;     } else if (MODE == E_UQ) {
; #pragma unroll
;       for (int j = 0; j < 8; ++j) v[j] *= q.s;
;       if (col % 192 >= 128) rope8v(v, q.a0, q.a1);
;       store8bf((bf16_t*)e.out + (size_t)row * NQ + col, v);
.LBB0_690:
	s_or_b64 exec, exec, s[16:17]
	v_mov_b64_e32 v[198:199], s[6:7]
	v_mov_b32_e32 v215, v214
	v_mad_i64_i32 v[198:199], s[0:1], v234, s83, v[198:199]
	v_ashrrev_i32_e32 v181, 31, v180
	v_lshl_add_u64 v[198:199], v[180:181], 1, v[198:199]
	v_cvt_pk_bf16_f32 v202, v202, v203
	v_cvt_pk_bf16_f32 v203, v204, v205
	v_cvt_pk_bf16_f32 v204, v216, v217
	v_cvt_pk_bf16_f32 v205, v200, v201
	v_pk_mul_f32 v[194:195], v[194:195], v[214:215]
	v_pk_mul_f32 v[196:197], v[196:197], v[214:215]
	v_pk_mul_f32 v[200:201], v[190:191], v[214:215]
	v_pk_mul_f32 v[192:193], v[192:193], v[214:215]
	global_store_dwordx4 v[198:199], v[202:205], off
	s_and_saveexec_b64 s[16:17], vcc
	s_cbranch_execz .LBB0_692
	s_waitcnt vmcnt(1)
	v_pk_mul_f32 v[190:191], v[194:195], v[158:159] op_sel:[1,1] op_sel_hi:[1,0]
	v_pk_mul_f32 v[202:203], v[194:195], v[158:159]
	v_pk_fma_f32 v[194:195], v[194:195], v[158:159], v[190:191] op_sel_hi:[0,1,1]
	v_pk_mul_f32 v[204:205], v[196:197], v[160:161] op_sel:[1,1] op_sel_hi:[1,0]
	v_mul_f32_e32 v194, v193, v157
	v_pk_fma_f32 v[214:215], v[196:197], v[160:161], v[204:205] op_sel_hi:[0,1,1] neg_lo:[0,0,1] neg_hi:[0,0,1]
	v_pk_fma_f32 v[196:197], v[196:197], v[160:161], v[204:205] op_sel_hi:[0,1,1]
	v_pk_mul_f32 v[204:205], v[200:201], v[154:155] op_sel:[1,1] op_sel_hi:[1,0]
	v_mov_b32_e32 v196, v214
	v_pk_fma_f32 v[216:217], v[200:201], v[154:155], v[204:205] op_sel_hi:[0,1,1] neg_lo:[0,0,1] neg_hi:[0,0,1]
	v_pk_fma_f32 v[200:201], v[200:201], v[154:155], v[204:205] op_sel_hi:[0,1,1]
	v_pk_fma_f32 v[204:205], v[192:193], v[156:157], v[194:195] op_sel_hi:[1,1,0] neg_lo:[0,0,1] neg_hi:[0,0,1]
	v_mul_f32_e32 v194, v193, v156
	v_pk_fma_f32 v[218:219], v[192:193], v[156:157], v[194:195] op_sel:[0,1,0] op_sel_hi:[1,0,0]
	v_sub_f32_e32 v194, v202, v190
	v_mov_b32_e32 v200, v216
	v_mov_b32_e32 v192, v204
	v_mov_b32_e32 v193, v218
.LBB0_692:
	s_or_b64 exec, exec, s[16:17]
	v_mul_f32_e32 v190, 0x3dd53b94, v212
	v_cvt_pk_bf16_f32 v194, v194, v195
	v_cvt_pk_bf16_f32 v195, v196, v197
	v_cvt_pk_bf16_f32 v196, v200, v201
	v_cvt_pk_bf16_f32 v197, v192, v193
	v_pk_mul_f32 v[186:187], v[186:187], v[190:191] op_sel_hi:[1,0]
	v_pk_mul_f32 v[188:189], v[188:189], v[190:191] op_sel_hi:[1,0]
	v_pk_mul_f32 v[192:193], v[182:183], v[190:191] op_sel_hi:[1,0]
	v_pk_mul_f32 v[184:185], v[184:185], v[190:191] op_sel_hi:[1,0]
	global_store_dwordx4 v[198:199], v[194:197], off offset:256
	s_and_saveexec_b64 s[16:17], s[4:5]
	s_cbranch_execz .LBB0_694
	s_waitcnt vmcnt(2)
	v_pk_mul_f32 v[182:183], v[186:187], v[150:151] op_sel:[1,1] op_sel_hi:[1,0]
	v_pk_mul_f32 v[194:195], v[186:187], v[150:151]
	v_pk_fma_f32 v[186:187], v[186:187], v[150:151], v[182:183] op_sel_hi:[0,1,1]
	v_pk_mul_f32 v[196:197], v[188:189], v[152:153] op_sel:[1,1] op_sel_hi:[1,0]
	v_mul_f32_e32 v186, v185, v149
	v_pk_fma_f32 v[198:199], v[188:189], v[152:153], v[196:197] op_sel_hi:[0,1,1] neg_lo:[0,0,1] neg_hi:[0,0,1]
	v_pk_fma_f32 v[188:189], v[188:189], v[152:153], v[196:197] op_sel_hi:[0,1,1]
	v_pk_mul_f32 v[196:197], v[192:193], v[146:147] op_sel:[1,1] op_sel_hi:[1,0]
	v_mov_b32_e32 v188, v198
	v_pk_fma_f32 v[200:201], v[192:193], v[146:147], v[196:197] op_sel_hi:[0,1,1] neg_lo:[0,0,1] neg_hi:[0,0,1]
	v_pk_fma_f32 v[192:193], v[192:193], v[146:147], v[196:197] op_sel_hi:[0,1,1]
	v_pk_fma_f32 v[196:197], v[184:185], v[148:149], v[186:187] op_sel_hi:[1,1,0] neg_lo:[0,0,1] neg_hi:[0,0,1]
	v_mul_f32_e32 v186, v185, v148
	v_pk_fma_f32 v[202:203], v[184:185], v[148:149], v[186:187] op_sel:[0,1,0] op_sel_hi:[1,0,0]
	v_sub_f32_e32 v186, v194, v182
	v_mov_b32_e32 v192, v200
	v_mov_b32_e32 v184, v196
	v_mov_b32_e32 v185, v202
.LBB0_694:
	s_or_b64 exec, exec, s[16:17]
	v_mov_b64_e32 v[182:183], s[6:7]
	v_mov_b32_e32 v191, v190
	v_mad_i64_i32 v[182:183], s[0:1], v240, s83, v[182:183]
	v_lshl_add_u64 v[182:183], v[180:181], 1, v[182:183]
	v_cvt_pk_bf16_f32 v186, v186, v187
	v_cvt_pk_bf16_f32 v187, v188, v189
	v_cvt_pk_bf16_f32 v188, v192, v193
	v_cvt_pk_bf16_f32 v189, v184, v185
	v_pk_mul_f32 v[166:167], v[166:167], v[190:191]
	v_pk_mul_f32 v[168:169], v[168:169], v[190:191]
	v_pk_mul_f32 v[184:185], v[162:163], v[190:191]
	v_pk_mul_f32 v[164:165], v[164:165], v[190:191]
	global_store_dwordx4 v[182:183], v[186:189], off
	s_and_saveexec_b64 s[16:17], vcc
	s_cbranch_execz .LBB0_696
	s_waitcnt vmcnt(3)
	v_pk_mul_f32 v[162:163], v[166:167], v[140:141] op_sel:[1,1] op_sel_hi:[1,0]
	v_pk_mul_f32 v[186:187], v[166:167], v[140:141]
	v_pk_fma_f32 v[166:167], v[166:167], v[140:141], v[162:163] op_sel_hi:[0,1,1]
	v_pk_mul_f32 v[188:189], v[168:169], v[142:143] op_sel:[1,1] op_sel_hi:[1,0]
	v_mul_f32_e32 v166, v165, v139
	v_pk_fma_f32 v[190:191], v[168:169], v[142:143], v[188:189] op_sel_hi:[0,1,1] neg_lo:[0,0,1] neg_hi:[0,0,1]
	v_pk_fma_f32 v[168:169], v[168:169], v[142:143], v[188:189] op_sel_hi:[0,1,1]
	v_pk_mul_f32 v[188:189], v[184:185], v[136:137] op_sel:[1,1] op_sel_hi:[1,0]
	v_mov_b32_e32 v168, v190
	v_pk_fma_f32 v[192:193], v[184:185], v[136:137], v[188:189] op_sel_hi:[0,1,1] neg_lo:[0,0,1] neg_hi:[0,0,1]
	v_pk_fma_f32 v[184:185], v[184:185], v[136:137], v[188:189] op_sel_hi:[0,1,1]
	v_pk_fma_f32 v[188:189], v[164:165], v[138:139], v[166:167] op_sel_hi:[1,1,0] neg_lo:[0,0,1] neg_hi:[0,0,1]
	v_mul_f32_e32 v166, v165, v138
	v_pk_fma_f32 v[194:195], v[164:165], v[138:139], v[166:167] op_sel:[0,1,0] op_sel_hi:[1,0,0]
	v_sub_f32_e32 v166, v186, v162
	v_mov_b32_e32 v184, v192
	v_mov_b32_e32 v164, v188
	v_mov_b32_e32 v165, v194

; __device__ __forceinline__ void rope8v(float (&v)[8], f32x4 c0, f32x4 c1) {
;   const float cs[8] = {c0[0], c0[1], c0[2], c0[3], c1[0], c1[1], c1[2], c1[3]};
; #pragma unroll
;   for (int i = 0; i < 4; ++i) { const float x1 = v[2 * i], x2 = v[2 * i + 1]; v[2 * i] = x1 * cs[2 * i] - x2 * cs[2 * i + 1]; v[2 * i + 1] = x2 * cs[2 * i] + x1 * cs[2 * i + 1]; }
; }
;   __device__ __forceinline__ void emit(const EpiPre& q0, int row, int col, f32x4 a, f32x4 b, const f32x4 (&hb)[2][2], const float (&hs)[2][4], int ai_, int m_, int bj_) const {
;     ...
;     } else if (MODE == E_UQ) {
; #pragma unroll
;       for (int j = 0; j < 8; ++j) v[j] *= q.s;
;       if (col % 192 >= 128) rope8v(v, q.a0, q.a1);
;       store8bf((bf16_t*)e.out + (size_t)row * NQ + col, v);
.LBB0_706:
	s_or_b64 exec, exec, s[16:17]
	v_mov_b64_e32 v[128:129], s[6:7]
	v_mov_b32_e32 v165, v164
	v_mad_i64_i32 v[128:129], s[0:1], v238, s83, v[128:129]
	v_lshl_add_u64 v[128:129], v[180:181], 1, v[128:129]
	v_cvt_pk_bf16_f32 v132, v132, v133
	v_cvt_pk_bf16_f32 v133, v134, v135
	v_cvt_pk_bf16_f32 v134, v166, v167
	v_cvt_pk_bf16_f32 v135, v130, v131
	v_pk_mul_f32 v[106:107], v[106:107], v[164:165]
	v_pk_mul_f32 v[108:109], v[108:109], v[164:165]
	v_pk_mul_f32 v[130:131], v[102:103], v[164:165]
	v_pk_mul_f32 v[104:105], v[104:105], v[164:165]
	global_store_dwordx4 v[128:129], v[132:135], off
	s_and_saveexec_b64 s[16:17], vcc
	s_cbranch_execz .LBB0_708
	s_waitcnt vmcnt(1)
	v_pk_mul_f32 v[102:103], v[106:107], v[116:117] op_sel:[1,1] op_sel_hi:[1,0]
	v_pk_mul_f32 v[132:133], v[106:107], v[116:117]
	v_pk_fma_f32 v[106:107], v[106:107], v[116:117], v[102:103] op_sel_hi:[0,1,1]
	v_pk_mul_f32 v[134:135], v[108:109], v[118:119] op_sel:[1,1] op_sel_hi:[1,0]
	v_mul_f32_e32 v106, v105, v115
	v_pk_fma_f32 v[164:165], v[108:109], v[118:119], v[134:135] op_sel_hi:[0,1,1] neg_lo:[0,0,1] neg_hi:[0,0,1]
	v_pk_fma_f32 v[108:109], v[108:109], v[118:119], v[134:135] op_sel_hi:[0,1,1]
	v_pk_mul_f32 v[134:135], v[130:131], v[112:113] op_sel:[1,1] op_sel_hi:[1,0]
	v_mov_b32_e32 v108, v164
	v_pk_fma_f32 v[166:167], v[130:131], v[112:113], v[134:135] op_sel_hi:[0,1,1] neg_lo:[0,0,1] neg_hi:[0,0,1]
	v_pk_fma_f32 v[130:131], v[130:131], v[112:113], v[134:135] op_sel_hi:[0,1,1]
	v_pk_fma_f32 v[134:135], v[104:105], v[114:115], v[106:107] op_sel_hi:[1,1,0] neg_lo:[0,0,1] neg_hi:[0,0,1]
	v_mul_f32_e32 v106, v105, v114
	v_pk_fma_f32 v[168:169], v[104:105], v[114:115], v[106:107] op_sel:[0,1,0] op_sel_hi:[1,0,0]
	v_sub_f32_e32 v106, v132, v102
	v_mov_b32_e32 v130, v166
	v_mov_b32_e32 v104, v134
	v_mov_b32_e32 v105, v168
.LBB0_708:
	s_or_b64 exec, exec, s[16:17]
	v_mul_f32_e32 v102, 0x3dd53b94, v206
	v_cvt_pk_bf16_f32 v106, v106, v107
	v_cvt_pk_bf16_f32 v107, v108, v109
	v_cvt_pk_bf16_f32 v108, v130, v131
	v_cvt_pk_bf16_f32 v109, v104, v105
	v_pk_mul_f32 v[86:87], v[86:87], v[102:103] op_sel_hi:[1,0]
	v_pk_mul_f32 v[88:89], v[88:89], v[102:103] op_sel_hi:[1,0]
	v_pk_mul_f32 v[104:105], v[82:83], v[102:103] op_sel_hi:[1,0]
	v_pk_mul_f32 v[84:85], v[84:85], v[102:103] op_sel_hi:[1,0]
	global_store_dwordx4 v[128:129], v[106:109], off offset:256
	s_and_saveexec_b64 s[16:17], s[4:5]
	s_cbranch_execz .LBB0_710
	s_waitcnt vmcnt(2)
	v_pk_mul_f32 v[82:83], v[86:87], v[98:99] op_sel:[1,1] op_sel_hi:[1,0]
	v_pk_mul_f32 v[106:107], v[86:87], v[98:99]
	v_pk_fma_f32 v[86:87], v[86:87], v[98:99], v[82:83] op_sel_hi:[0,1,1]
	v_pk_mul_f32 v[108:109], v[88:89], v[100:101] op_sel:[1,1] op_sel_hi:[1,0]
	v_mul_f32_e32 v86, v85, v93
	v_pk_fma_f32 v[128:129], v[88:89], v[100:101], v[108:109] op_sel_hi:[0,1,1] neg_lo:[0,0,1] neg_hi:[0,0,1]
	v_pk_fma_f32 v[88:89], v[88:89], v[100:101], v[108:109] op_sel_hi:[0,1,1]
	v_pk_mul_f32 v[108:109], v[104:105], v[90:91] op_sel:[1,1] op_sel_hi:[1,0]
	v_mov_b32_e32 v88, v128
	v_pk_fma_f32 v[130:131], v[104:105], v[90:91], v[108:109] op_sel_hi:[0,1,1] neg_lo:[0,0,1] neg_hi:[0,0,1]
	v_pk_fma_f32 v[104:105], v[104:105], v[90:91], v[108:109] op_sel_hi:[0,1,1]
	v_pk_fma_f32 v[108:109], v[84:85], v[92:93], v[86:87] op_sel_hi:[1,1,0] neg_lo:[0,0,1] neg_hi:[0,0,1]
	v_mul_f32_e32 v86, v85, v92
	v_pk_fma_f32 v[132:133], v[84:85], v[92:93], v[86:87] op_sel:[0,1,0] op_sel_hi:[1,0,0]
	v_sub_f32_e32 v86, v106, v82
	v_mov_b32_e32 v104, v130
	v_mov_b32_e32 v84, v108
	v_mov_b32_e32 v85, v132
.LBB0_710:
	s_or_b64 exec, exec, s[16:17]
	v_mov_b64_e32 v[82:83], s[6:7]
	v_mov_b32_e32 v103, v102
	v_mad_i64_i32 v[82:83], s[0:1], v236, s83, v[82:83]
	v_lshl_add_u64 v[82:83], v[180:181], 1, v[82:83]
	v_cvt_pk_bf16_f32 v86, v86, v87
	v_cvt_pk_bf16_f32 v87, v88, v89
	v_cvt_pk_bf16_f32 v88, v104, v105
	v_cvt_pk_bf16_f32 v89, v84, v85
	v_pk_mul_f32 v[68:69], v[68:69], v[102:103]
	v_pk_mul_f32 v[70:71], v[70:71], v[102:103]
	v_pk_mul_f32 v[64:65], v[64:65], v[102:103]
	v_pk_mul_f32 v[66:67], v[66:67], v[102:103]
	global_store_dwordx4 v[82:83], v[86:89], off
	s_and_saveexec_b64 s[16:17], vcc
	s_cbranch_execz .LBB0_712
	s_waitcnt vmcnt(3)
	v_pk_mul_f32 v[88:89], v[70:71], v[80:81] op_sel:[1,1] op_sel_hi:[1,0]
	v_pk_mul_f32 v[84:85], v[68:69], v[78:79] op_sel:[1,1] op_sel_hi:[1,0]
	v_pk_fma_f32 v[102:103], v[70:71], v[80:81], v[88:89] op_sel_hi:[0,1,1] neg_lo:[0,0,1] neg_hi:[0,0,1]
	v_pk_fma_f32 v[70:71], v[70:71], v[80:81], v[88:89] op_sel_hi:[0,1,1]
	v_pk_mul_f32 v[88:89], v[64:65], v[74:75] op_sel:[1,1] op_sel_hi:[1,0]
	v_pk_mul_f32 v[86:87], v[68:69], v[78:79]
	v_pk_fma_f32 v[104:105], v[64:65], v[74:75], v[88:89] op_sel_hi:[0,1,1] neg_lo:[0,0,1] neg_hi:[0,0,1]
	v_pk_fma_f32 v[64:65], v[64:65], v[74:75], v[88:89] op_sel_hi:[0,1,1]
	v_mul_f32_e32 v64, v67, v77
	v_pk_fma_f32 v[88:89], v[66:67], v[76:77], v[64:65] op_sel_hi:[1,1,0] neg_lo:[0,0,1] neg_hi:[0,0,1]
	v_mul_f32_e32 v64, v67, v76
	v_pk_fma_f32 v[68:69], v[68:69], v[78:79], v[84:85] op_sel_hi:[0,1,1]
	v_pk_fma_f32 v[106:107], v[66:67], v[76:77], v[64:65] op_sel:[0,1,0] op_sel_hi:[1,0,0]
	v_sub_f32_e32 v68, v86, v84
	v_mov_b32_e32 v70, v102
	v_mov_b32_e32 v64, v104
	v_mov_b32_e32 v66, v88
	v_mov_b32_e32 v67, v106

; __device__ __forceinline__ void rope8v(float (&v)[8], f32x4 c0, f32x4 c1) {
;   const float cs[8] = {c0[0], c0[1], c0[2], c0[3], c1[0], c1[1], c1[2], c1[3]};
; #pragma unroll
;   for (int i = 0; i < 4; ++i) { const float x1 = v[2 * i], x2 = v[2 * i + 1]; v[2 * i] = x1 * cs[2 * i] - x2 * cs[2 * i + 1]; v[2 * i + 1] = x2 * cs[2 * i] + x1 * cs[2 * i + 1]; }
; }
;   __device__ __forceinline__ void emit(const EpiPre& q0, int row, int col, f32x4 a, f32x4 b, const f32x4 (&hb)[2][2], const float (&hs)[2][4], int ai_, int m_, int bj_) const {
;     ...
;     } else if (MODE == E_UQ) {
; #pragma unroll
;       for (int j = 0; j < 8; ++j) v[j] *= q.s;
;       if (col % 192 >= 128) rope8v(v, q.a0, q.a1);
;       store8bf((bf16_t*)e.out + (size_t)row * NQ + col, v);
.LBB0_722:
	s_or_b64 exec, exec, s[16:17]
	v_mov_b64_e32 v[56:57], s[6:7]
	v_mov_b32_e32 v65, v64
	v_mad_i64_i32 v[56:57], s[0:1], v162, s83, v[56:57]
	v_lshl_add_u64 v[56:57], v[180:181], 1, v[56:57]
	v_cvt_pk_bf16_f32 v60, v60, v61
	v_cvt_pk_bf16_f32 v61, v62, v63
	v_cvt_pk_bf16_f32 v62, v66, v67
	v_cvt_pk_bf16_f32 v63, v58, v59
	v_pk_mul_f32 v[52:53], v[52:53], v[64:65]
	v_pk_mul_f32 v[54:55], v[54:55], v[64:65]
	v_pk_mul_f32 v[58:59], v[48:49], v[64:65]
	v_pk_mul_f32 v[50:51], v[50:51], v[64:65]
	global_store_dwordx4 v[56:57], v[60:63], off
	s_and_saveexec_b64 s[16:17], vcc
	s_cbranch_execz .LBB0_724
	s_waitcnt vmcnt(1)
	v_pk_mul_f32 v[48:49], v[52:53], v[158:159] op_sel:[1,1] op_sel_hi:[1,0]
	v_pk_mul_f32 v[60:61], v[52:53], v[158:159]
	v_pk_fma_f32 v[52:53], v[52:53], v[158:159], v[48:49] op_sel_hi:[0,1,1]
	v_pk_mul_f32 v[62:63], v[54:55], v[160:161] op_sel:[1,1] op_sel_hi:[1,0]
	v_mul_f32_e32 v52, v51, v157
	v_pk_fma_f32 v[64:65], v[54:55], v[160:161], v[62:63] op_sel_hi:[0,1,1] neg_lo:[0,0,1] neg_hi:[0,0,1]
	v_pk_fma_f32 v[54:55], v[54:55], v[160:161], v[62:63] op_sel_hi:[0,1,1]
	v_pk_mul_f32 v[62:63], v[58:59], v[154:155] op_sel:[1,1] op_sel_hi:[1,0]
	v_mov_b32_e32 v54, v64
	v_pk_fma_f32 v[66:67], v[58:59], v[154:155], v[62:63] op_sel_hi:[0,1,1] neg_lo:[0,0,1] neg_hi:[0,0,1]
	v_pk_fma_f32 v[58:59], v[58:59], v[154:155], v[62:63] op_sel_hi:[0,1,1]
	v_pk_fma_f32 v[62:63], v[50:51], v[156:157], v[52:53] op_sel_hi:[1,1,0] neg_lo:[0,0,1] neg_hi:[0,0,1]
	v_mul_f32_e32 v52, v51, v156
	v_pk_fma_f32 v[68:69], v[50:51], v[156:157], v[52:53] op_sel:[0,1,0] op_sel_hi:[1,0,0]
	v_sub_f32_e32 v52, v60, v48
	v_mov_b32_e32 v58, v66
	v_mov_b32_e32 v50, v62
	v_mov_b32_e32 v51, v68
.LBB0_724:
	s_or_b64 exec, exec, s[16:17]
	v_mul_f32_e32 v48, 0x3dd53b94, v144
	v_cvt_pk_bf16_f32 v52, v52, v53
	v_cvt_pk_bf16_f32 v53, v54, v55
	v_cvt_pk_bf16_f32 v54, v58, v59
	v_cvt_pk_bf16_f32 v55, v50, v51
	v_pk_mul_f32 v[44:45], v[44:45], v[48:49] op_sel_hi:[1,0]
	v_pk_mul_f32 v[46:47], v[46:47], v[48:49] op_sel_hi:[1,0]
	v_pk_mul_f32 v[50:51], v[40:41], v[48:49] op_sel_hi:[1,0]
	v_pk_mul_f32 v[42:43], v[42:43], v[48:49] op_sel_hi:[1,0]
	global_store_dwordx4 v[56:57], v[52:55], off offset:256
	s_and_saveexec_b64 s[16:17], s[4:5]
	s_cbranch_execz .LBB0_726
	s_waitcnt vmcnt(2)
	v_pk_mul_f32 v[40:41], v[44:45], v[150:151] op_sel:[1,1] op_sel_hi:[1,0]
	v_pk_mul_f32 v[52:53], v[44:45], v[150:151]
	v_pk_fma_f32 v[44:45], v[44:45], v[150:151], v[40:41] op_sel_hi:[0,1,1]
	v_pk_mul_f32 v[54:55], v[46:47], v[152:153] op_sel:[1,1] op_sel_hi:[1,0]
	v_mul_f32_e32 v44, v43, v149
	v_pk_fma_f32 v[56:57], v[46:47], v[152:153], v[54:55] op_sel_hi:[0,1,1] neg_lo:[0,0,1] neg_hi:[0,0,1]
	v_pk_fma_f32 v[46:47], v[46:47], v[152:153], v[54:55] op_sel_hi:[0,1,1]
	v_pk_mul_f32 v[54:55], v[50:51], v[146:147] op_sel:[1,1] op_sel_hi:[1,0]
	v_mov_b32_e32 v46, v56
	v_pk_fma_f32 v[58:59], v[50:51], v[146:147], v[54:55] op_sel_hi:[0,1,1] neg_lo:[0,0,1] neg_hi:[0,0,1]
	v_pk_fma_f32 v[50:51], v[50:51], v[146:147], v[54:55] op_sel_hi:[0,1,1]
	v_pk_fma_f32 v[54:55], v[42:43], v[148:149], v[44:45] op_sel_hi:[1,1,0] neg_lo:[0,0,1] neg_hi:[0,0,1]
	v_mul_f32_e32 v44, v43, v148
	v_pk_fma_f32 v[60:61], v[42:43], v[148:149], v[44:45] op_sel:[0,1,0] op_sel_hi:[1,0,0]
	v_sub_f32_e32 v44, v52, v40
	v_mov_b32_e32 v50, v58
	v_mov_b32_e32 v42, v54
	v_mov_b32_e32 v43, v60
.LBB0_726:
	s_or_b64 exec, exec, s[16:17]
	v_add_u32_e32 v52, 0x90, v234
	v_mov_b64_e32 v[40:41], s[6:7]
	v_mov_b32_e32 v49, v48
	v_mad_i64_i32 v[40:41], s[0:1], v52, s83, v[40:41]
	v_lshl_add_u64 v[40:41], v[180:181], 1, v[40:41]
	v_cvt_pk_bf16_f32 v44, v44, v45
	v_cvt_pk_bf16_f32 v45, v46, v47
	v_cvt_pk_bf16_f32 v46, v50, v51
	v_cvt_pk_bf16_f32 v47, v42, v43
	v_pk_mul_f32 v[36:37], v[36:37], v[48:49]
	v_pk_mul_f32 v[38:39], v[38:39], v[48:49]
	v_pk_mul_f32 v[42:43], v[32:33], v[48:49]
	v_pk_mul_f32 v[34:35], v[34:35], v[48:49]
	global_store_dwordx4 v[40:41], v[44:47], off
	s_and_saveexec_b64 s[16:17], vcc
	s_cbranch_execz .LBB0_728
	s_waitcnt vmcnt(3)
	v_pk_mul_f32 v[32:33], v[36:37], v[140:141] op_sel:[1,1] op_sel_hi:[1,0]
	v_pk_mul_f32 v[44:45], v[36:37], v[140:141]
	v_pk_fma_f32 v[36:37], v[36:37], v[140:141], v[32:33] op_sel_hi:[0,1,1]
	v_pk_mul_f32 v[46:47], v[38:39], v[142:143] op_sel:[1,1] op_sel_hi:[1,0]
	v_mul_f32_e32 v36, v35, v139
	v_pk_fma_f32 v[48:49], v[38:39], v[142:143], v[46:47] op_sel_hi:[0,1,1] neg_lo:[0,0,1] neg_hi:[0,0,1]
	v_pk_fma_f32 v[38:39], v[38:39], v[142:143], v[46:47] op_sel_hi:[0,1,1]
	v_pk_mul_f32 v[46:47], v[42:43], v[136:137] op_sel:[1,1] op_sel_hi:[1,0]
	v_mov_b32_e32 v38, v48
	v_pk_fma_f32 v[50:51], v[42:43], v[136:137], v[46:47] op_sel_hi:[0,1,1] neg_lo:[0,0,1] neg_hi:[0,0,1]
	v_pk_fma_f32 v[42:43], v[42:43], v[136:137], v[46:47] op_sel_hi:[0,1,1]
	v_pk_fma_f32 v[46:47], v[34:35], v[138:139], v[36:37] op_sel_hi:[1,1,0] neg_lo:[0,0,1] neg_hi:[0,0,1]
	v_mul_f32_e32 v36, v35, v138
	v_pk_fma_f32 v[52:53], v[34:35], v[138:139], v[36:37] op_sel:[0,1,0] op_sel_hi:[1,0,0]
	v_sub_f32_e32 v36, v44, v32
	v_mov_b32_e32 v42, v50
	v_mov_b32_e32 v34, v46
	v_mov_b32_e32 v35, v52
; __device__ __forceinline__ void rope8v(float (&v)[8], f32x4 c0, f32x4 c1) {
;   const float cs[8] = {c0[0], c0[1], c0[2], c0[3], c1[0], c1[1], c1[2], c1[3]};
; #pragma unroll
;   for (int i = 0; i < 4; ++i) { const float x1 = v[2 * i], x2 = v[2 * i + 1]; v[2 * i] = x1 * cs[2 * i] - x2 * cs[2 * i + 1]; v[2 * i + 1] = x2 * cs[2 * i] + x1 * cs[2 * i + 1]; }
; }
;   __device__ __forceinline__ void emit(const EpiPre& q0, int row, int col, f32x4 a, f32x4 b, const f32x4 (&hb)[2][2], const float (&hs)[2][4], int ai_, int m_, int bj_) const {
;     ...
;     } else if (MODE == E_UQ) {
; #pragma unroll
;       for (int j = 0; j < 8; ++j) v[j] *= q.s;
;       if (col % 192 >= 128) rope8v(v, q.a0, q.a1);
;       store8bf((bf16_t*)e.out + (size_t)row * NQ + col, v);
.LBB0_728:
	s_or_b64 exec, exec, s[16:17]
	v_cvt_pk_bf16_f32 v36, v36, v37
	v_cvt_pk_bf16_f32 v37, v38, v39
	v_cvt_pk_bf16_f32 v38, v42, v43
	v_cvt_pk_bf16_f32 v39, v34, v35
	global_store_dwordx4 v[40:41], v[36:39], off offset:256
	v_mul_f32_e32 v32, 0x3dd53b94, v110
	v_pk_mul_f32 v[28:29], v[28:29], v[32:33] op_sel_hi:[1,0]
	v_pk_mul_f32 v[30:31], v[30:31], v[32:33] op_sel_hi:[1,0]
	v_pk_mul_f32 v[34:35], v[24:25], v[32:33] op_sel_hi:[1,0]
	v_pk_mul_f32 v[26:27], v[26:27], v[32:33] op_sel_hi:[1,0]
	s_and_saveexec_b64 s[16:17], s[4:5]
	s_cbranch_execz .LBB0_730
	s_waitcnt vmcnt(4)
	v_pk_mul_f32 v[24:25], v[28:29], v[124:125] op_sel:[1,1] op_sel_hi:[1,0]
	v_pk_mul_f32 v[36:37], v[28:29], v[124:125]
	v_pk_fma_f32 v[28:29], v[28:29], v[124:125], v[24:25] op_sel_hi:[0,1,1]
	v_pk_mul_f32 v[38:39], v[30:31], v[126:127] op_sel:[1,1] op_sel_hi:[1,0]
	v_mul_f32_e32 v28, v27, v123
	v_pk_fma_f32 v[40:41], v[30:31], v[126:127], v[38:39] op_sel_hi:[0,1,1] neg_lo:[0,0,1] neg_hi:[0,0,1]
	v_pk_fma_f32 v[30:31], v[30:31], v[126:127], v[38:39] op_sel_hi:[0,1,1]
	v_pk_mul_f32 v[38:39], v[34:35], v[120:121] op_sel:[1,1] op_sel_hi:[1,0]
	v_mov_b32_e32 v30, v40
	v_pk_fma_f32 v[42:43], v[34:35], v[120:121], v[38:39] op_sel_hi:[0,1,1] neg_lo:[0,0,1] neg_hi:[0,0,1]
	v_pk_fma_f32 v[34:35], v[34:35], v[120:121], v[38:39] op_sel_hi:[0,1,1]
	v_pk_fma_f32 v[38:39], v[26:27], v[122:123], v[28:29] op_sel_hi:[1,1,0] neg_lo:[0,0,1] neg_hi:[0,0,1]
	v_mul_f32_e32 v28, v27, v122
	v_pk_fma_f32 v[44:45], v[26:27], v[122:123], v[28:29] op_sel:[0,1,0] op_sel_hi:[1,0,0]
	v_sub_f32_e32 v28, v36, v24
	v_mov_b32_e32 v34, v42
	v_mov_b32_e32 v26, v38
	v_mov_b32_e32 v27, v44
.LBB0_730:
	s_or_b64 exec, exec, s[16:17]
	v_add_u32_e32 v36, 0xa0, v234
	v_mov_b64_e32 v[24:25], s[6:7]
	v_mov_b32_e32 v33, v32
	v_mad_i64_i32 v[24:25], s[0:1], v36, s83, v[24:25]
	v_lshl_add_u64 v[24:25], v[180:181], 1, v[24:25]
	v_cvt_pk_bf16_f32 v28, v28, v29
	v_cvt_pk_bf16_f32 v29, v30, v31
	v_cvt_pk_bf16_f32 v30, v34, v35
	v_cvt_pk_bf16_f32 v31, v26, v27
	v_pk_mul_f32 v[20:21], v[20:21], v[32:33]
	v_pk_mul_f32 v[22:23], v[22:23], v[32:33]
	v_pk_mul_f32 v[26:27], v[16:17], v[32:33]
	v_pk_mul_f32 v[18:19], v[18:19], v[32:33]
	global_store_dwordx4 v[24:25], v[28:31], off
	s_and_saveexec_b64 s[16:17], vcc
	s_cbranch_execz .LBB0_732
	s_waitcnt vmcnt(5)
	v_pk_mul_f32 v[16:17], v[20:21], v[116:117] op_sel:[1,1] op_sel_hi:[1,0]
	v_pk_mul_f32 v[28:29], v[20:21], v[116:117]
	v_pk_fma_f32 v[20:21], v[20:21], v[116:117], v[16:17] op_sel_hi:[0,1,1]
	v_pk_mul_f32 v[30:31], v[22:23], v[118:119] op_sel:[1,1] op_sel_hi:[1,0]
	v_mul_f32_e32 v20, v19, v115
	v_pk_fma_f32 v[32:33], v[22:23], v[118:119], v[30:31] op_sel_hi:[0,1,1] neg_lo:[0,0,1] neg_hi:[0,0,1]
	v_pk_fma_f32 v[22:23], v[22:23], v[118:119], v[30:31] op_sel_hi:[0,1,1]
	v_pk_mul_f32 v[30:31], v[26:27], v[112:113] op_sel:[1,1] op_sel_hi:[1,0]
	v_mov_b32_e32 v22, v32
	v_pk_fma_f32 v[34:35], v[26:27], v[112:113], v[30:31] op_sel_hi:[0,1,1] neg_lo:[0,0,1] neg_hi:[0,0,1]
	v_pk_fma_f32 v[26:27], v[26:27], v[112:113], v[30:31] op_sel_hi:[0,1,1]
	v_pk_fma_f32 v[30:31], v[18:19], v[114:115], v[20:21] op_sel_hi:[1,1,0] neg_lo:[0,0,1] neg_hi:[0,0,1]
	v_mul_f32_e32 v20, v19, v114
	v_pk_fma_f32 v[36:37], v[18:19], v[114:115], v[20:21] op_sel:[0,1,0] op_sel_hi:[1,0,0]
	v_sub_f32_e32 v20, v28, v16
	v_mov_b32_e32 v26, v34
	v_mov_b32_e32 v18, v30
	v_mov_b32_e32 v19, v36
.LBB0_732:
	s_or_b64 exec, exec, s[16:17]
	v_mul_f32_e32 v16, 0x3dd53b94, v72
	v_cvt_pk_bf16_f32 v20, v20, v21
	v_cvt_pk_bf16_f32 v21, v22, v23
	v_cvt_pk_bf16_f32 v22, v26, v27
	v_cvt_pk_bf16_f32 v23, v18, v19
	v_pk_mul_f32 v[12:13], v[12:13], v[16:17] op_sel_hi:[1,0]
	v_pk_mul_f32 v[14:15], v[14:15], v[16:17] op_sel_hi:[1,0]
	v_pk_mul_f32 v[18:19], v[8:9], v[16:17] op_sel_hi:[1,0]
	v_pk_mul_f32 v[10:11], v[10:11], v[16:17] op_sel_hi:[1,0]
	global_store_dwordx4 v[24:25], v[20:23], off offset:256
	s_and_saveexec_b64 s[16:17], s[4:5]
	s_cbranch_execz .LBB0_734
	s_waitcnt vmcnt(6)
	v_pk_mul_f32 v[8:9], v[12:13], v[98:99] op_sel:[1,1] op_sel_hi:[1,0]
	v_pk_mul_f32 v[20:21], v[12:13], v[98:99]
	v_pk_fma_f32 v[12:13], v[12:13], v[98:99], v[8:9] op_sel_hi:[0,1,1]
	v_pk_mul_f32 v[22:23], v[14:15], v[100:101] op_sel:[1,1] op_sel_hi:[1,0]
	v_mul_f32_e32 v12, v11, v93
	v_pk_fma_f32 v[24:25], v[14:15], v[100:101], v[22:23] op_sel_hi:[0,1,1] neg_lo:[0,0,1] neg_hi:[0,0,1]
	v_pk_fma_f32 v[14:15], v[14:15], v[100:101], v[22:23] op_sel_hi:[0,1,1]
	v_pk_mul_f32 v[22:23], v[18:19], v[90:91] op_sel:[1,1] op_sel_hi:[1,0]
	v_mov_b32_e32 v14, v24
	v_pk_fma_f32 v[26:27], v[18:19], v[90:91], v[22:23] op_sel_hi:[0,1,1] neg_lo:[0,0,1] neg_hi:[0,0,1]
	v_pk_fma_f32 v[18:19], v[18:19], v[90:91], v[22:23] op_sel_hi:[0,1,1]
	v_pk_fma_f32 v[22:23], v[10:11], v[92:93], v[12:13] op_sel_hi:[1,1,0] neg_lo:[0,0,1] neg_hi:[0,0,1]
	v_mul_f32_e32 v12, v11, v92
	v_pk_fma_f32 v[28:29], v[10:11], v[92:93], v[12:13] op_sel:[0,1,0] op_sel_hi:[1,0,0]
	v_sub_f32_e32 v12, v20, v8
	v_mov_b32_e32 v18, v26
	v_mov_b32_e32 v10, v22
	v_mov_b32_e32 v11, v28
.LBB0_734:
	s_or_b64 exec, exec, s[16:17]
	v_add_u32_e32 v20, 0xb0, v234
	v_mov_b64_e32 v[8:9], s[6:7]
	v_mov_b32_e32 v17, v16
	v_mad_i64_i32 v[8:9], s[0:1], v20, s83, v[8:9]
	v_lshl_add_u64 v[8:9], v[180:181], 1, v[8:9]
	v_cvt_pk_bf16_f32 v12, v12, v13
	v_cvt_pk_bf16_f32 v13, v14, v15
	v_cvt_pk_bf16_f32 v14, v18, v19
	v_cvt_pk_bf16_f32 v15, v10, v11
	v_pk_mul_f32 v[4:5], v[4:5], v[16:17]
	v_pk_mul_f32 v[6:7], v[6:7], v[16:17]
	v_pk_mul_f32 v[0:1], v[0:1], v[16:17]
	v_pk_mul_f32 v[2:3], v[2:3], v[16:17]
	global_store_dwordx4 v[8:9], v[12:15], off
	s_and_saveexec_b64 s[4:5], vcc
	s_cbranch_execz .LBB0_665
	s_waitcnt vmcnt(7)
	v_pk_mul_f32 v[14:15], v[6:7], v[80:81] op_sel:[1,1] op_sel_hi:[1,0]
	v_pk_mul_f32 v[10:11], v[4:5], v[78:79] op_sel:[1,1] op_sel_hi:[1,0]
	v_pk_fma_f32 v[16:17], v[6:7], v[80:81], v[14:15] op_sel_hi:[0,1,1] neg_lo:[0,0,1] neg_hi:[0,0,1]
	v_pk_fma_f32 v[6:7], v[6:7], v[80:81], v[14:15] op_sel_hi:[0,1,1]
	v_pk_mul_f32 v[14:15], v[0:1], v[74:75] op_sel:[1,1] op_sel_hi:[1,0]
	v_pk_mul_f32 v[12:13], v[4:5], v[78:79]
	v_pk_fma_f32 v[18:19], v[0:1], v[74:75], v[14:15] op_sel_hi:[0,1,1] neg_lo:[0,0,1] neg_hi:[0,0,1]
	v_pk_fma_f32 v[0:1], v[0:1], v[74:75], v[14:15] op_sel_hi:[0,1,1]
	v_mul_f32_e32 v0, v3, v77
	v_pk_fma_f32 v[14:15], v[2:3], v[76:77], v[0:1] op_sel_hi:[1,1,0] neg_lo:[0,0,1] neg_hi:[0,0,1]
	v_mul_f32_e32 v0, v3, v76
	v_pk_fma_f32 v[4:5], v[4:5], v[78:79], v[10:11] op_sel_hi:[0,1,1]
	v_pk_fma_f32 v[20:21], v[2:3], v[76:77], v[0:1] op_sel:[0,1,0] op_sel_hi:[1,0,0]
	v_sub_f32_e32 v4, v12, v10
	v_mov_b32_e32 v6, v16
	v_mov_b32_e32 v0, v18
	v_mov_b32_e32 v2, v14
	v_mov_b32_e32 v3, v20
	s_branch .LBB0_665
